# v20 + LayerNorm row loops: next-row prefetch no longer waited on immediately (one wait before the loop, counted wait where the prefetched row is copied)
# baseline (speedup 1.0000x reference)
; DEVI int tidx() { int t = threadIdx.x; asm volatile("" : "+v"(t)); return t; }
; DEVI f32x4 ldnt4(const float* p_) { return __builtin_nontemporal_load((const f32x4*)p_); }
;   const int lane = tidx() & 63, w = tidx() >> 6;
;   float* xf = (float*)(p.ws + WS_XF);
;   u16* xb = (u16*)(p.ws + WS_XB);
;   float4 gg[4], bb[4];
; #pragma unroll
;   for (int i = 0; i < 4; i++) { gg[i] = ((const float4*)g)[lane + 64 * i]; bb[i] = ((const float4*)b)[lane + 64 * i]; }
;   const int rstep = gridDim.x * 4;
;   int r = blockIdx.x * 4 + w;
;   float4 v[4], vn[4];
;   if (r < T_ALL) {
;     const float* src = (mode == 0) ? (r < T_P ? p.x_prompt + (size_t)r * 1024 : p.x_sample + (size_t)(r - T_P) * 1024) : xf + (size_t)r * 1024;
; #pragma unroll
;     for (int i = 0; i < 4; i++) { if (mode == 0) { const f32x4 t4 = ldnt4(src + (size_t)(lane + 64 * i) * 4); v[i] = make_float4(t4[0], t4[1], t4[2], t4[3]); } else v[i] = ((const float4*)src)[lane + 64 * i]; }
;   }
;   for (; r < T_ALL; r += rstep) {
;     const int rn = r + rstep;
;     if (rn < T_ALL) {
;       const float* srcn = (mode == 0) ? (rn < T_P ? p.x_prompt + (size_t)rn * 1024 : p.x_sample + (size_t)(rn - T_P) * 1024) : xf + (size_t)rn * 1024;
; #pragma unroll
;       for (int i = 0; i < 4; i++) { if (mode == 0) { const f32x4 t4 = ldnt4(srcn + (size_t)(lane + 64 * i) * 4); vn[i] = make_float4(t4[0], t4[1], t4[2], t4[3]); } else vn[i] = ((const float4*)srcn)[lane + 64 * i]; }
;     }
.LBB0_10:
	v_readlane_b32 s0, v254, 61
	s_add_i32 s0, s0, 0xffff
	s_and_b32 s2, s0, 0xff
	s_mulk_i32 s2, 0x4f
	s_bfe_u32 s2, s2, 0x6000a
	v_writelane_b32 v254, s2, 62
	s_mul_i32 s2, s2, 13
	s_sub_i32 s0, s0, s2
	s_and_b32 s0, s0, 0xff
	v_writelane_b32 v254, s0, 63
	s_cmp_lt_i32 s0, 7
	s_mov_b64 s[2:3], -1
	s_cbranch_scc1 .LBB0_712
	v_readlane_b32 s0, v254, 63
	s_and_b32 s0, 0xffff, s0
	s_cmp_lt_i32 s0, 10
	s_cbranch_scc1 .LBB0_132
	s_cmp_lt_i32 s0, 11
	s_cbranch_scc1 .LBB0_121
	s_cmp_gt_i32 s0, 11
	s_cbranch_scc0 .LBB0_38
	v_mov_b32_e32 v2, v145
	v_mov_b32_e32 v0, v145
	v_readlane_b32 s2, v254, 23
	v_ashrrev_i32_e32 v0, 6, v0
	s_nop 0
	v_add_u32_e32 v84, s2, v0
	s_movk_i32 s2, 0x4200
	v_cmp_gt_i32_e32 vcc, s2, v84
	s_and_saveexec_b64 s[8:9], vcc
	s_cbranch_execz .LBB0_37
	v_readlane_b32 s2, v254, 61
	s_cmp_lt_u32 s2, 40
	v_readlane_b32 s2, v254, 62
	v_readlane_b32 s36, v250, 45
	s_cselect_b64 s[10:11], -1, 0
	s_lshl_b32 s4, s2, 12
	v_readlane_b32 s50, v250, 59
	v_readlane_b32 s37, v250, 46
	v_readlane_b32 s38, v250, 47
	v_readlane_b32 s39, v250, 48
	v_readlane_b32 s40, v250, 49
	v_readlane_b32 s41, v250, 50
	v_readlane_b32 s42, v250, 51
	v_readlane_b32 s43, v250, 52
	v_readlane_b32 s51, v250, 60
	s_add_u32 s2, s50, s4
	s_addc_u32 s3, s51, 0
	v_readlane_b32 s36, v250, 1
	s_waitcnt vmcnt(0)
	v_and_b32_e32 v34, 63, v2
	v_readlane_b32 s37, v250, 2
	s_add_u32 s4, s36, s4
	v_lshlrev_b32_e32 v66, 4, v34
	s_addc_u32 s5, s37, 0
	global_load_dwordx4 v[2:5], v66, s[2:3]
	global_load_dwordx4 v[6:9], v66, s[2:3] offset:1024
	global_load_dwordx4 v[10:13], v66, s[4:5]
	global_load_dwordx4 v[14:17], v66, s[4:5] offset:1024
	global_load_dwordx4 v[18:21], v66, s[2:3] offset:2048
	global_load_dwordx4 v[22:25], v66, s[2:3] offset:3072
	global_load_dwordx4 v[26:29], v66, s[4:5] offset:2048
	s_waitcnt lgkmcnt(0)
	global_load_dwordx4 v[30:33], v66, s[4:5] offset:3072
	v_ashrrev_i32_e32 v85, 31, v84
	v_readlane_b32 s40, v250, 5
	v_readlane_b32 s41, v250, 6
	v_lshlrev_b64 v[36:37], 12, v[84:85]
	v_mov_b32_e32 v67, v1
	v_lshl_add_u64 v[38:39], s[40:41], 0, v[36:37]
	v_lshl_add_u64 v[38:39], v[38:39], 0, v[66:67]
	global_load_dwordx4 v[62:65], v[38:39], off
	global_load_dwordx4 v[58:61], v[38:39], off offset:1024
	global_load_dwordx4 v[54:57], v[38:39], off offset:2048
	global_load_dwordx4 v[50:53], v[38:39], off offset:3072
	v_xor_b32_e32 v35, 32, v151
	v_cmp_lt_i32_e32 vcc, v35, v160
	v_readlane_b32 s38, v250, 3
	v_readlane_b32 s39, v250, 4
	v_cndmask_b32_e32 v35, v151, v35, vcc
	v_lshlrev_b32_e32 v108, 2, v35
	v_xor_b32_e32 v35, 16, v151
	v_cmp_lt_i32_e32 vcc, v35, v160
	v_readlane_b32 s2, v254, 24
	v_lshl_add_u64 v[68:69], s[38:39], 0, v[36:37]
	v_cndmask_b32_e32 v35, v151, v35, vcc
	v_lshlrev_b32_e32 v109, 2, v35
	v_xor_b32_e32 v35, 8, v151
	v_cmp_lt_i32_e32 vcc, v35, v160
	v_add_u32_e32 v36, s2, v0
	v_or_b32_e32 v38, 64, v34
	v_cndmask_b32_e32 v35, v151, v35, vcc
	v_lshlrev_b32_e32 v110, 2, v35
	v_xor_b32_e32 v35, 4, v151
	v_cmp_lt_i32_e32 vcc, v35, v160
	v_or_b32_e32 v40, 0x80, v34
	v_or_b32_e32 v42, 0xc0, v34
	v_cndmask_b32_e32 v35, v151, v35, vcc
	v_lshlrev_b32_e32 v111, 2, v35
	v_xor_b32_e32 v35, 2, v151
	v_cmp_lt_i32_e32 vcc, v35, v160
	v_lshlrev_b64 v[70:71], 11, v[84:85]
	v_ashrrev_i32_e32 v37, 31, v36
	v_cndmask_b32_e32 v35, v151, v35, vcc
	v_lshlrev_b32_e32 v112, 2, v35
	v_xor_b32_e32 v35, 1, v151
	v_cmp_lt_i32_e32 vcc, v35, v160
	v_lshl_or_b32 v70, v34, 3, v70
	v_lshlrev_b64 v[72:73], 12, v[36:37]
	v_cndmask_b32_e32 v35, v151, v35, vcc
	v_lshlrev_b32_e32 v113, 2, v35
	v_lshl_add_u64 v[74:75], s[40:41], 0, v[66:67]
	s_mov_b64 s[12:13], 0
	v_lshlrev_b32_e32 v76, 4, v34
	v_lshlrev_b32_e32 v78, 4, v38
	v_lshlrev_b32_e32 v80, 4, v40
	v_lshlrev_b32_e32 v82, 4, v42
	v_readlane_b32 s44, v250, 53
	v_readlane_b32 s45, v250, 54
	v_readlane_b32 s46, v250, 55
	v_readlane_b32 s47, v250, 56
	v_readlane_b32 s48, v250, 57
	v_readlane_b32 s49, v250, 58
	v_readlane_b32 s42, v250, 7
	v_readlane_b32 s43, v250, 8
	s_waitcnt vmcnt(0)
	s_branch .LBB0_17
.LBB0_16:
	s_waitcnt vmcnt(4)
	s_and_b64 s[2:3], exec, s[4:5]
	s_or_b64 s[12:13], s[2:3], s[12:13]
	v_readlane_b32 s2, v254, 17
	v_readlane_b32 s4, v254, 19
	v_readlane_b32 s3, v254, 18
	v_readlane_b32 s5, v254, 20
	v_mov_b32_e32 v84, v114
	v_lshl_add_u64 v[68:69], v[68:69], 0, s[2:3]
	v_lshl_add_u64 v[70:71], v[70:71], 0, s[4:5]
	v_lshl_add_u64 v[72:73], v[72:73], 0, s[2:3]
	v_mov_b64_e32 v[50:51], v[46:47]
	v_mov_b64_e32 v[52:53], v[48:49]
	v_mov_b64_e32 v[54:55], v[42:43]
	v_mov_b64_e32 v[56:57], v[44:45]
	v_mov_b64_e32 v[58:59], v[38:39]
	v_mov_b64_e32 v[60:61], v[40:41]
	v_mov_b64_e32 v[62:63], v[34:35]
	v_mov_b64_e32 v[64:65], v[36:37]
	s_andn2_b64 exec, exec, s[12:13]
	s_cbranch_execz .LBB0_37

; DEVI unsigned pack2(float a, float b) { return __builtin_bit_cast(unsigned, __builtin_convertvector((f32x2_t){a, b}, bf16x2_t)); }
; DEVI void stnt4(float* p_, f32x4 v) { __builtin_nontemporal_store(v, (f32x4*)p_); }
;     ...
;     float s = 0.f, q = 0.f;
; #pragma unroll
;     for (int i = 0; i < 4; i++) {
;       s += v[i].x + v[i].y + v[i].z + v[i].w;
;       q += v[i].x * v[i].x + v[i].y * v[i].y + v[i].z * v[i].z + v[i].w * v[i].w;
;     }
; #pragma unroll
;     for (int o = 32; o > 0; o >>= 1) { const float s2 = __shfl_xor(s, o), q2 = __shfl_xor(q, o); s += s2; q += q2; }
;     const float mu = s * (1.f / 1024.f);
;     const float var = fmaxf(q * (1.f / 1024.f) - mu * mu, 0.f);
;     const float rs = rsqrtf(var + 1e-5f);
; #pragma unroll
;     for (int i = 0; i < 4; i++) {
;       float4 o;
;       o.x = (v[i].x - mu) * rs * gg[i].x + bb[i].x; o.y = (v[i].y - mu) * rs * gg[i].y + bb[i].y;
;       o.z = (v[i].z - mu) * rs * gg[i].z + bb[i].z; o.w = (v[i].w - mu) * rs * gg[i].w + bb[i].w;
;       uint2 pk; pk.x = pack2(o.x, o.y); pk.y = pack2(o.z, o.w);
;       if (mode != 2) ((uint2*)(xb + (size_t)r * 1024))[lane + 64 * i] = pk;
;       if (mode == 2) stnt4(p.out + O_Y + (size_t)r * 1024 + (size_t)(lane + 64 * i) * 4, (f32x4){o.x, o.y, o.z, o.w});
;     }
.LBB0_21:
	s_or_b64 exec, exec, s[6:7]
	v_pk_add_f32 v[84:85], v[62:63], v[62:63] op_sel:[0,1] op_sel_hi:[1,0]
	v_pk_mul_f32 v[86:87], v[62:63], v[62:63]
	v_mul_f32_e32 v0, v59, v59
	v_pk_mul_f32 v[88:89], v[64:65], v[64:65]
	v_pk_add_f32 v[90:91], v[58:59], v[58:59] op_sel_hi:[0,1]
	v_pk_fma_f32 v[92:93], v[58:59], v[58:59], v[0:1] op_sel_hi:[1,1,0]
	v_pk_mul_f32 v[94:95], v[60:61], v[60:61]
	v_mul_f32_e32 v0, v55, v55
	v_mov_b32_e32 v116, v86
	v_mov_b32_e32 v117, v84
	v_pk_mov_b32 v[84:85], v[86:87], v[64:65] op_sel:[1,0]
	v_pk_fma_f32 v[98:99], v[54:55], v[54:55], v[0:1] op_sel_hi:[1,1,0]
	v_mul_f32_e32 v0, v51, v51
	v_pk_add_f32 v[84:85], v[116:117], v[84:85]
	v_mov_b32_e32 v86, v88
	v_mov_b32_e32 v87, v65
	v_mov_b32_e32 v90, v94
	v_mov_b32_e32 v93, v60
	v_pk_add_f32 v[96:97], v[54:55], v[54:55] op_sel_hi:[0,1]
	v_pk_mul_f32 v[100:101], v[56:57], v[56:57]
	v_pk_fma_f32 v[104:105], v[50:51], v[50:51], v[0:1] op_sel_hi:[1,1,0]
	v_pk_add_f32 v[84:85], v[84:85], v[86:87]
	v_mov_b32_e32 v0, v89
	v_pk_add_f32 v[86:87], v[90:91], v[92:93]
	v_mov_b32_e32 v88, v95
	v_mov_b32_e32 v89, v61
	v_pk_add_f32 v[84:85], v[84:85], v[0:1]
	v_pk_add_f32 v[86:87], v[86:87], v[88:89]
	v_mov_b32_e32 v96, v100
	v_mov_b32_e32 v99, v56
	v_pk_add_f32 v[102:103], v[50:51], v[50:51] op_sel_hi:[0,1]
	v_pk_mul_f32 v[106:107], v[52:53], v[52:53]
	v_pk_add_f32 v[84:85], v[84:85], v[86:87]
	v_pk_add_f32 v[86:87], v[96:97], v[98:99]
	v_mov_b32_e32 v88, v101
	v_mov_b32_e32 v89, v57
	v_pk_add_f32 v[86:87], v[86:87], v[88:89]
	v_mov_b32_e32 v102, v106
	v_mov_b32_e32 v105, v52
	v_pk_add_f32 v[84:85], v[84:85], v[86:87]
	v_pk_add_f32 v[86:87], v[102:103], v[104:105]
	v_mov_b32_e32 v88, v107
	v_mov_b32_e32 v89, v53
	v_pk_add_f32 v[86:87], v[86:87], v[88:89]
	s_mov_b32 s2, 0x3a800000
	v_pk_add_f32 v[84:85], v[84:85], v[86:87]
	ds_bpermute_b32 v87, v108, v85
	ds_bpermute_b32 v86, v108, v84
	v_readlane_b32 s36, v250, 1
	v_readlane_b32 s40, v250, 5
	v_readlane_b32 s41, v250, 6
	v_readlane_b32 s37, v250, 2
	s_waitcnt lgkmcnt(0)
	v_pk_add_f32 v[84:85], v[84:85], v[86:87]
	ds_bpermute_b32 v87, v109, v85
	ds_bpermute_b32 v86, v109, v84
	v_lshl_add_u64 v[88:89], s[40:41], 0, v[70:71]
	v_lshrrev_b32_e32 v172, 25, v70
	v_xor_b32_e32 v172, 1, v172
	v_bfe_u32 v173, v70, 11, 1
	v_mul_u32_u24_e32 v173, 0x7c0, v173
	v_bfe_u32 v164, v145, 3, 3
	v_lshlrev_b32_e32 v164, 6, v164
	v_sub_u32_e32 v164, v164, v173
	v_mul_i32_i24_e32 v164, v164, v172
	v_lshlrev_b32_e32 v173, 9, v172
	v_add_u32_e32 v166, v164, v173
	v_add_u32_e32 v168, v166, v173
	v_add_u32_e32 v170, v168, v173
	v_ashrrev_i32_e32 v165, 31, v164
	v_ashrrev_i32_e32 v167, 31, v166
	v_ashrrev_i32_e32 v169, 31, v168
	v_ashrrev_i32_e32 v171, 31, v170
	v_readlane_b32 s38, v250, 3
	v_readlane_b32 s39, v250, 4
	v_readlane_b32 s42, v250, 7
	s_waitcnt lgkmcnt(0)
	v_pk_add_f32 v[84:85], v[84:85], v[86:87]
	ds_bpermute_b32 v87, v110, v85
	ds_bpermute_b32 v86, v110, v84
	v_readlane_b32 s43, v250, 8
	s_waitcnt lgkmcnt(0)
	v_pk_add_f32 v[84:85], v[84:85], v[86:87]
	ds_bpermute_b32 v87, v111, v85
	ds_bpermute_b32 v86, v111, v84
	s_waitcnt lgkmcnt(0)
	v_pk_add_f32 v[84:85], v[84:85], v[86:87]
	ds_bpermute_b32 v87, v112, v85
	ds_bpermute_b32 v86, v112, v84
	s_waitcnt lgkmcnt(0)
	v_pk_add_f32 v[84:85], v[84:85], v[86:87]
	ds_bpermute_b32 v87, v113, v85
	ds_bpermute_b32 v86, v113, v84
	s_waitcnt lgkmcnt(0)
	v_pk_add_f32 v[84:85], v[84:85], v[86:87]
	s_nop 0
	v_pk_mul_f32 v[84:85], v[84:85], s[2:3] op_sel_hi:[1,0]
	s_mov_b32 s2, 0x800000
	v_fma_f32 v0, -v85, v85, v84
	v_max_f32_e32 v0, 0, v0
	v_add_f32_e32 v0, 0x3727c5ac, v0
	v_mul_f32_e32 v77, 0x4b800000, v0
	v_cmp_gt_f32_e32 vcc, s2, v0
	v_pk_add_f32 v[62:63], v[62:63], v[84:85] op_sel:[0,1] neg_lo:[0,1] neg_hi:[0,1]
	v_pk_add_f32 v[64:65], v[64:65], v[84:85] op_sel:[0,1] neg_lo:[0,1] neg_hi:[0,1]
	v_cndmask_b32_e32 v0, v0, v77, vcc
	v_rsq_f32_e32 v0, v0
	s_mov_b64 s[2:3], -1
	v_mul_f32_e32 v77, 0x45800000, v0
	v_cndmask_b32_e32 v86, v0, v77, vcc
	v_pk_mul_f32 v[62:63], v[62:63], v[86:87] op_sel_hi:[1,0]
	v_pk_mul_f32 v[64:65], v[64:65], v[86:87] op_sel_hi:[1,0]
	v_cndmask_b32_e64 v0, 0, 1, s[10:11]
	v_pk_fma_f32 v[62:63], v[2:3], v[62:63], v[10:11]
	v_pk_fma_f32 v[64:65], v[4:5], v[64:65], v[12:13]
	v_cmp_ne_u32_e64 s[6:7], 1, v0
	s_andn2_b64 vcc, exec, s[10:11]
	s_cbranch_vccnz .LBB0_23
	v_add_co_u32_e32 v92, vcc, 0x4200000, v88
	v_cvt_pk_bf16_f32 v91, v64, v65
	v_cvt_pk_bf16_f32 v90, v62, v63
	v_addc_co_u32_e32 v93, vcc, 0, v89, vcc
	v_lshl_add_u64 v[92:93], v[92:93], 0, v[164:165]
	s_mov_b64 s[2:3], 0
	global_store_dwordx2 v[92:93], v[90:91], off

; DEVI int tidx() { int t = threadIdx.x; asm volatile("" : "+v"(t)); return t; }
; DEVI f32x4 ldnt4(const float* p_) { return __builtin_nontemporal_load((const f32x4*)p_); }
;   const int lane = tidx() & 63, w = tidx() >> 6;
;   float* xf = (float*)(p.ws + WS_XF);
;   u16* xb = (u16*)(p.ws + WS_XB);
;   float4 gg[4], bb[4];
; #pragma unroll
;   for (int i = 0; i < 4; i++) { gg[i] = ((const float4*)g)[lane + 64 * i]; bb[i] = ((const float4*)b)[lane + 64 * i]; }
;   const int rstep = gridDim.x * 4;
;   int r = blockIdx.x * 4 + w;
;   float4 v[4], vn[4];
;   if (r < T_ALL) {
;     const float* src = (mode == 0) ? (r < T_P ? p.x_prompt + (size_t)r * 1024 : p.x_sample + (size_t)(r - T_P) * 1024) : xf + (size_t)r * 1024;
; #pragma unroll
;     for (int i = 0; i < 4; i++) { if (mode == 0) { const f32x4 t4 = ldnt4(src + (size_t)(lane + 64 * i) * 4); v[i] = make_float4(t4[0], t4[1], t4[2], t4[3]); } else v[i] = ((const float4*)src)[lane + 64 * i]; }
;   }
;   for (; r < T_ALL; r += rstep) {
;     const int rn = r + rstep;
;     if (rn < T_ALL) {
;       const float* srcn = (mode == 0) ? (rn < T_P ? p.x_prompt + (size_t)rn * 1024 : p.x_sample + (size_t)(rn - T_P) * 1024) : xf + (size_t)rn * 1024;
; #pragma unroll
;       for (int i = 0; i < 4; i++) { if (mode == 0) { const f32x4 t4 = ldnt4(srcn + (size_t)(lane + 64 * i) * 4); vn[i] = make_float4(t4[0], t4[1], t4[2], t4[3]); } else vn[i] = ((const float4*)srcn)[lane + 64 * i]; }
;     }
.LBB0_132:
	s_andn2_b64 vcc, exec, s[2:3]
	s_cbranch_vccnz .LBB0_711
	s_cmp_lt_i32 s0, 8
	s_mov_b64 s[2:3], -1
	s_cbranch_scc1 .LBB0_225
	s_cmp_gt_i32 s0, 8
	s_cbranch_scc0 .LBB0_143
	v_mov_b32_e32 v0, v145
	v_mov_b32_e32 v2, v145
	v_readlane_b32 s0, v254, 23
	s_waitcnt vmcnt(0)
	v_ashrrev_i32_e32 v34, 6, v2
	v_add_u32_e32 v78, s0, v34
	s_movk_i32 s0, 0x4200
	v_cmp_gt_i32_e32 vcc, s0, v78
	s_and_saveexec_b64 s[6:7], vcc
	s_cbranch_execz .LBB0_142
	v_readlane_b32 s0, v254, 62
	v_readlane_b32 s36, v250, 45
	s_lshl_b32 s0, s0, 12
	v_readlane_b32 s40, v250, 49
	v_readlane_b32 s41, v250, 50
	s_add_u32 s2, s40, s0
	v_readlane_b32 s42, v250, 51
	s_addc_u32 s3, s41, 0
	v_and_b32_e32 v36, 63, v0
	v_readlane_b32 s43, v250, 52
	s_add_u32 s4, s42, s0
	v_lshlrev_b32_e32 v0, 4, v36
	s_addc_u32 s5, s43, 0
	global_load_dwordx4 v[2:5], v0, s[2:3]
	global_load_dwordx4 v[6:9], v0, s[2:3] offset:1024
	global_load_dwordx4 v[10:13], v0, s[4:5]
	global_load_dwordx4 v[14:17], v0, s[4:5] offset:1024
	global_load_dwordx4 v[18:21], v0, s[2:3] offset:2048
	global_load_dwordx4 v[22:25], v0, s[2:3] offset:3072
	global_load_dwordx4 v[26:29], v0, s[4:5] offset:2048
	s_waitcnt lgkmcnt(0)
	global_load_dwordx4 v[30:33], v0, s[4:5] offset:3072
	v_ashrrev_i32_e32 v79, 31, v78
	v_readlane_b32 s8, v250, 1
	v_lshlrev_b64 v[38:39], 12, v[78:79]
	v_readlane_b32 s12, v250, 5
	v_readlane_b32 s13, v250, 6
	v_xor_b32_e32 v35, 32, v151
	v_cmp_lt_i32_e32 vcc, v35, v160
	v_lshl_add_u64 v[38:39], s[12:13], 0, v[38:39]
	v_lshl_add_u64 v[38:39], v[38:39], 0, v[0:1]
	global_load_dwordx4 v[58:61], v[38:39], off
	global_load_dwordx4 v[50:53], v[38:39], off offset:1024
	global_load_dwordx4 v[54:57], v[38:39], off offset:2048
	global_load_dwordx4 v[62:65], v[38:39], off offset:3072
	v_cndmask_b32_e32 v35, v151, v35, vcc
	v_lshlrev_b32_e32 v80, 2, v35
	v_xor_b32_e32 v35, 16, v151
	v_cmp_lt_i32_e32 vcc, v35, v160
	v_readlane_b32 s0, v254, 24
	v_readlane_b32 s9, v250, 2
	v_cndmask_b32_e32 v35, v151, v35, vcc
	v_lshlrev_b32_e32 v81, 2, v35
	v_xor_b32_e32 v35, 8, v151
	v_cmp_lt_i32_e32 vcc, v35, v160
	v_add_u32_e32 v34, s0, v34
	v_or_b32_e32 v38, 64, v36
	v_cndmask_b32_e32 v35, v151, v35, vcc
	v_lshlrev_b32_e32 v82, 2, v35
	v_xor_b32_e32 v35, 4, v151
	v_cmp_lt_i32_e32 vcc, v35, v160
	v_or_b32_e32 v40, 0x80, v36
	v_or_b32_e32 v42, 0xc0, v36
	v_cndmask_b32_e32 v35, v151, v35, vcc
	v_lshlrev_b32_e32 v83, 2, v35
	v_xor_b32_e32 v35, 2, v151
	v_cmp_lt_i32_e32 vcc, v35, v160
	v_lshlrev_b64 v[66:67], 11, v[78:79]
	v_lshl_or_b32 v66, v36, 3, v66
	v_cndmask_b32_e32 v35, v151, v35, vcc
	v_lshlrev_b32_e32 v84, 2, v35
	v_xor_b32_e32 v35, 1, v151
	v_cmp_lt_i32_e32 vcc, v35, v160
	s_mov_b64 s[8:9], 0
	v_lshlrev_b32_e32 v70, 4, v36
	v_cndmask_b32_e32 v35, v151, v35, vcc
	v_lshlrev_b32_e32 v85, 2, v35
	v_ashrrev_i32_e32 v35, 31, v34
	v_lshlrev_b64 v[68:69], 12, v[34:35]
	v_or_b32_e32 v68, v68, v0
	v_lshlrev_b32_e32 v72, 4, v38
	v_lshlrev_b32_e32 v74, 4, v40
	v_lshlrev_b32_e32 v76, 4, v42
	v_readlane_b32 s37, v250, 46
	v_readlane_b32 s38, v250, 47
	v_readlane_b32 s39, v250, 48
	v_readlane_b32 s44, v250, 53
	v_readlane_b32 s45, v250, 54
	v_readlane_b32 s46, v250, 55
	v_readlane_b32 s47, v250, 56
	v_readlane_b32 s48, v250, 57
	v_readlane_b32 s49, v250, 58
	v_readlane_b32 s50, v250, 59
	v_readlane_b32 s51, v250, 60
	v_readlane_b32 s10, v250, 3
	v_readlane_b32 s11, v250, 4
	v_readlane_b32 s14, v250, 7
	v_readlane_b32 s15, v250, 8
	s_waitcnt vmcnt(0)
	s_branch .LBB0_138
; DEVI unsigned pack2(float a, float b) { return __builtin_bit_cast(unsigned, __builtin_convertvector((f32x2_t){a, b}, bf16x2_t)); }
; DEVI void stnt4(float* p_, f32x4 v) { __builtin_nontemporal_store(v, (f32x4*)p_); }
;     ...
;     float s = 0.f, q = 0.f;
; #pragma unroll
;     for (int i = 0; i < 4; i++) {
;       s += v[i].x + v[i].y + v[i].z + v[i].w;
;       q += v[i].x * v[i].x + v[i].y * v[i].y + v[i].z * v[i].z + v[i].w * v[i].w;
;     }
; #pragma unroll
;     for (int o = 32; o > 0; o >>= 1) { const float s2 = __shfl_xor(s, o), q2 = __shfl_xor(q, o); s += s2; q += q2; }
;     const float mu = s * (1.f / 1024.f);
;     const float var = fmaxf(q * (1.f / 1024.f) - mu * mu, 0.f);
;     const float rs = rsqrtf(var + 1e-5f);
; #pragma unroll
;     for (int i = 0; i < 4; i++) {
;       float4 o;
;       o.x = (v[i].x - mu) * rs * gg[i].x + bb[i].x; o.y = (v[i].y - mu) * rs * gg[i].y + bb[i].y;
;       o.z = (v[i].z - mu) * rs * gg[i].z + bb[i].z; o.w = (v[i].w - mu) * rs * gg[i].w + bb[i].w;
;       uint2 pk; pk.x = pack2(o.x, o.y); pk.y = pack2(o.z, o.w);
;       if (mode != 2) ((uint2*)(xb + (size_t)r * 1024))[lane + 64 * i] = pk;
;       if (mode == 2) stnt4(p.out + O_Y + (size_t)r * 1024 + (size_t)(lane + 64 * i) * 4, (f32x4){o.x, o.y, o.z, o.w});
;     }
; #pragma unroll
;     for (int i = 0; i < 4; i++) v[i] = vn[i];
.LBB0_137:
	s_or_b64 exec, exec, s[10:11]
	v_mul_f32_e32 v0, v51, v51
	v_pk_fma_f32 v[88:89], v[50:51], v[50:51], v[0:1] op_sel_hi:[1,1,0]
	v_mul_f32_e32 v0, v55, v55
	v_pk_fma_f32 v[92:93], v[54:55], v[54:55], v[0:1] op_sel_hi:[1,1,0]
	v_mov_b32_e32 v102, v64
	v_mov_b32_e32 v103, v62
	v_mul_f32_e32 v0, v63, v63
	v_pk_fma_f32 v[104:105], v[62:63], v[62:63], v[0:1] op_sel_hi:[1,1,0]
	v_pk_mul_f32 v[106:107], v[64:65], v[64:65]
	v_pk_add_f32 v[102:103], v[102:103], v[62:63]
	v_mov_b32_e32 v105, v64
	v_mov_b32_e32 v107, v103
	v_mul_f32_e32 v94, v65, v65
	v_pk_add_f32 v[96:97], v[58:59], v[58:59] op_sel:[0,1] op_sel_hi:[1,0]
	v_pk_mul_f32 v[98:99], v[58:59], v[58:59]
	v_pk_mul_f32 v[100:101], v[60:61], v[60:61]
	v_pk_add_f32 v[102:103], v[106:107], v[104:105]
	v_mov_b32_e32 v95, v65
	v_pk_add_f32 v[86:87], v[50:51], v[50:51] op_sel_hi:[0,1]
	v_pk_add_f32 v[94:95], v[102:103], v[94:95]
	v_mov_b32_e32 v102, v98
	v_mov_b32_e32 v103, v96
	v_pk_mov_b32 v[96:97], v[98:99], v[60:61] op_sel:[1,0]
	v_mov_b32_e32 v98, v100
	v_mov_b32_e32 v0, v101
	v_pk_mul_f32 v[100:101], v[52:53], v[52:53]
	v_mov_b32_e32 v89, v52
	v_mov_b32_e32 v86, v100
	v_pk_add_f32 v[86:87], v[86:87], v[88:89]
	v_mov_b32_e32 v88, v101
	v_mov_b32_e32 v89, v53
	v_pk_add_f32 v[90:91], v[54:55], v[54:55] op_sel_hi:[0,1]
	v_pk_add_f32 v[96:97], v[102:103], v[96:97]
	v_mov_b32_e32 v99, v61
	v_pk_add_f32 v[86:87], v[86:87], v[88:89]
	v_pk_mul_f32 v[88:89], v[56:57], v[56:57]
	v_pk_add_f32 v[96:97], v[96:97], v[98:99]
	v_mov_b32_e32 v90, v88
	v_mov_b32_e32 v93, v56
	v_pk_add_f32 v[96:97], v[96:97], v[0:1]
	v_pk_add_f32 v[90:91], v[90:91], v[92:93]
	v_mov_b32_e32 v88, v89
	v_mov_b32_e32 v89, v57
	v_pk_add_f32 v[86:87], v[96:97], v[86:87]
	v_pk_add_f32 v[88:89], v[90:91], v[88:89]
	s_mov_b32 s0, 0x3a800000
	v_pk_add_f32 v[86:87], v[86:87], v[88:89]
	s_and_b64 s[2:3], exec, vcc
	v_pk_add_f32 v[86:87], v[86:87], v[94:95]
	ds_bpermute_b32 v89, v80, v87
	ds_bpermute_b32 v88, v80, v86
	v_readlane_b32 s36, v250, 1
	v_readlane_b32 s40, v250, 5
	v_readlane_b32 s41, v250, 6
	s_or_b64 s[8:9], s[2:3], s[8:9]
	s_waitcnt lgkmcnt(0)
	v_pk_add_f32 v[86:87], v[86:87], v[88:89]
	ds_bpermute_b32 v89, v81, v87
	ds_bpermute_b32 v88, v81, v86
	v_lshl_add_u64 v[98:99], s[40:41], 0, v[66:67]
	v_lshrrev_b32_e32 v118, 25, v66
	v_xor_b32_e32 v118, 1, v118
	v_bfe_u32 v119, v66, 11, 1
	v_mul_u32_u24_e32 v119, 0x7c0, v119
	v_bfe_u32 v110, v145, 3, 3
	v_lshlrev_b32_e32 v110, 6, v110
	v_sub_u32_e32 v110, v110, v119
	v_mul_i32_i24_e32 v110, v110, v118
	v_lshlrev_b32_e32 v119, 9, v118
	v_add_u32_e32 v112, v110, v119
	v_add_u32_e32 v114, v112, v119
	v_add_u32_e32 v116, v114, v119
	v_ashrrev_i32_e32 v111, 31, v110
	v_ashrrev_i32_e32 v113, 31, v112
	v_ashrrev_i32_e32 v115, 31, v114
	v_ashrrev_i32_e32 v117, 31, v116
	v_readlane_b32 s2, v254, 19
	v_readlane_b32 s3, v254, 20
	v_mov_b32_e32 v78, v79
	s_waitcnt lgkmcnt(0)
	v_pk_add_f32 v[86:87], v[86:87], v[88:89]
	ds_bpermute_b32 v89, v82, v87
	ds_bpermute_b32 v88, v82, v86
	v_lshl_add_u64 v[66:67], v[66:67], 0, s[2:3]
	v_readlane_b32 s2, v254, 17
	v_readlane_b32 s3, v254, 18
	v_readlane_b32 s37, v250, 2
	s_waitcnt lgkmcnt(0)
	v_pk_add_f32 v[86:87], v[86:87], v[88:89]
	ds_bpermute_b32 v89, v83, v87
	ds_bpermute_b32 v88, v83, v86
	v_lshl_add_u64 v[68:69], v[68:69], 0, s[2:3]
	v_readlane_b32 s38, v250, 3
	v_readlane_b32 s39, v250, 4
	v_readlane_b32 s42, v250, 7
	s_waitcnt lgkmcnt(0)
	v_pk_add_f32 v[86:87], v[86:87], v[88:89]
	ds_bpermute_b32 v89, v84, v87
	ds_bpermute_b32 v88, v84, v86
	v_readlane_b32 s43, v250, 8
	s_waitcnt lgkmcnt(0)
	v_pk_add_f32 v[86:87], v[86:87], v[88:89]
	ds_bpermute_b32 v89, v85, v87
	ds_bpermute_b32 v88, v85, v86
	s_waitcnt lgkmcnt(0)
	v_pk_add_f32 v[86:87], v[86:87], v[88:89]
	s_nop 0
	v_pk_mul_f32 v[86:87], v[86:87], s[0:1] op_sel_hi:[1,0]
	s_mov_b32 s0, 0x800000
	v_fma_f32 v0, -v87, v87, v86
	v_max_f32_e32 v0, 0, v0
	v_add_f32_e32 v0, 0x3727c5ac, v0
	v_cmp_gt_f32_e32 vcc, s0, v0
	v_mul_f32_e32 v71, 0x4b800000, v0
	v_pk_add_f32 v[58:59], v[58:59], v[86:87] op_sel:[0,1] neg_lo:[0,1] neg_hi:[0,1]
	v_cndmask_b32_e32 v0, v0, v71, vcc
	v_rsq_f32_e32 v0, v0
	v_pk_add_f32 v[60:61], v[60:61], v[86:87] op_sel:[0,1] neg_lo:[0,1] neg_hi:[0,1]
	v_pk_add_f32 v[50:51], v[50:51], v[86:87] op_sel:[0,1] neg_lo:[0,1] neg_hi:[0,1]
	v_pk_add_f32 v[52:53], v[52:53], v[86:87] op_sel:[0,1] neg_lo:[0,1] neg_hi:[0,1]
	v_mul_f32_e32 v71, 0x45800000, v0
	v_cndmask_b32_e32 v0, v0, v71, vcc
	v_pk_mul_f32 v[58:59], v[58:59], v[0:1] op_sel_hi:[1,0]
	v_pk_mul_f32 v[60:61], v[60:61], v[0:1] op_sel_hi:[1,0]
	v_pk_fma_f32 v[58:59], v[2:3], v[58:59], v[10:11]
	v_pk_fma_f32 v[60:61], v[4:5], v[60:61], v[12:13]
	s_mov_b32 s0, 0x4200000
	v_pk_mul_f32 v[50:51], v[50:51], v[0:1] op_sel_hi:[1,0]
	v_pk_mul_f32 v[52:53], v[52:53], v[0:1] op_sel_hi:[1,0]
	v_cvt_pk_bf16_f32 v61, v60, v61
	v_cvt_pk_bf16_f32 v60, v58, v59
	v_add_co_u32_e32 v58, vcc, s0, v98
	v_pk_fma_f32 v[50:51], v[6:7], v[50:51], v[14:15]
	v_pk_fma_f32 v[52:53], v[8:9], v[52:53], v[16:17]
	v_addc_co_u32_e32 v59, vcc, 0, v99, vcc
	v_cvt_pk_bf16_f32 v53, v52, v53
	v_cvt_pk_bf16_f32 v52, v50, v51
	v_lshl_add_u64 v[118:119], v[58:59], 0, v[112:113]
	global_store_dwordx2 v[118:119], v[52:53], off offset:512
	v_pk_add_f32 v[50:51], v[54:55], v[86:87] op_sel:[0,1] neg_lo:[0,1] neg_hi:[0,1]
	v_pk_add_f32 v[52:53], v[56:57], v[86:87] op_sel:[0,1] neg_lo:[0,1] neg_hi:[0,1]
	v_pk_mul_f32 v[50:51], v[50:51], v[0:1] op_sel_hi:[1,0]
	v_pk_mul_f32 v[52:53], v[52:53], v[0:1] op_sel_hi:[1,0]
	v_pk_fma_f32 v[50:51], v[18:19], v[50:51], v[26:27]
	v_pk_fma_f32 v[52:53], v[20:21], v[52:53], v[28:29]
	v_lshl_add_u64 v[118:119], v[58:59], 0, v[110:111]
	global_store_dwordx2 v[118:119], v[60:61], off
	v_cvt_pk_bf16_f32 v53, v52, v53
	v_cvt_pk_bf16_f32 v52, v50, v51
	v_lshl_add_u64 v[118:119], v[58:59], 0, v[114:115]
	global_store_dwordx2 v[118:119], v[52:53], off offset:1024
	v_pk_add_f32 v[50:51], v[62:63], v[86:87] op_sel:[0,1] neg_lo:[0,1] neg_hi:[0,1]
	v_pk_add_f32 v[52:53], v[64:65], v[86:87] op_sel:[0,1] neg_lo:[0,1] neg_hi:[0,1]
	v_pk_mul_f32 v[50:51], v[50:51], v[0:1] op_sel_hi:[1,0]
	v_pk_mul_f32 v[52:53], v[52:53], v[0:1] op_sel_hi:[1,0]
	v_pk_fma_f32 v[50:51], v[22:23], v[50:51], v[30:31]
	v_pk_fma_f32 v[52:53], v[24:25], v[52:53], v[32:33]
	s_waitcnt vmcnt(3)
	v_mov_b64_e32 v[60:61], v[36:37]
	v_cvt_pk_bf16_f32 v53, v52, v53
	v_cvt_pk_bf16_f32 v52, v50, v51
	v_lshl_add_u64 v[118:119], v[58:59], 0, v[116:117]
	global_store_dwordx2 v[118:119], v[52:53], off offset:1536
	v_mov_b64_e32 v[58:59], v[34:35]
	v_mov_b64_e32 v[50:51], v[38:39]
	v_mov_b64_e32 v[52:53], v[40:41]
	v_mov_b64_e32 v[54:55], v[42:43]
	v_mov_b64_e32 v[56:57], v[44:45]
	v_mov_b64_e32 v[62:63], v[46:47]
	v_mov_b64_e32 v[64:65], v[48:49]
	s_andn2_b64 exec, exec, s[8:9]
	s_cbranch_execz .LBB0_142

; DEVI int tidx() { int t = threadIdx.x; asm volatile("" : "+v"(t)); return t; }
; DEVI f32x4 ldnt4(const float* p_) { return __builtin_nontemporal_load((const f32x4*)p_); }
;   const int lane = tidx() & 63, w = tidx() >> 6;
;   float* xf = (float*)(p.ws + WS_XF);
;   u16* xb = (u16*)(p.ws + WS_XB);
;   float4 gg[4], bb[4];
; #pragma unroll
;   for (int i = 0; i < 4; i++) { gg[i] = ((const float4*)g)[lane + 64 * i]; bb[i] = ((const float4*)b)[lane + 64 * i]; }
;   const int rstep = gridDim.x * 4;
;   int r = blockIdx.x * 4 + w;
;   float4 v[4], vn[4];
;   if (r < T_ALL) {
;     const float* src = (mode == 0) ? (r < T_P ? p.x_prompt + (size_t)r * 1024 : p.x_sample + (size_t)(r - T_P) * 1024) : xf + (size_t)r * 1024;
; #pragma unroll
;     for (int i = 0; i < 4; i++) { if (mode == 0) { const f32x4 t4 = ldnt4(src + (size_t)(lane + 64 * i) * 4); v[i] = make_float4(t4[0], t4[1], t4[2], t4[3]); } else v[i] = ((const float4*)src)[lane + 64 * i]; }
;   }
.LBB0_744:
	s_andn2_b64 vcc, exec, s[2:3]
	s_cbranch_vccnz .LBB0_753
	v_mov_b32_e32 v0, v145
	v_mov_b32_e32 v2, v145
	v_readlane_b32 s0, v254, 23
	s_waitcnt vmcnt(0)
	v_ashrrev_i32_e32 v34, 6, v2
	v_add_u32_e32 v78, s0, v34
	s_movk_i32 s0, 0x4200
	v_cmp_gt_i32_e32 vcc, s0, v78
	s_and_saveexec_b64 s[6:7], vcc
	s_cbranch_execz .LBB0_752
	v_readlane_b32 s0, v254, 62
	v_readlane_b32 s40, v250, 29
	s_lshl_b32 s0, s0, 12
	v_readlane_b32 s48, v250, 37
	v_readlane_b32 s49, v250, 38
	s_add_u32 s2, s48, s0
	v_readlane_b32 s50, v250, 39
	s_addc_u32 s3, s49, 0
	v_and_b32_e32 v36, 63, v0
	v_readlane_b32 s51, v250, 40
	s_add_u32 s4, s50, s0
	v_lshlrev_b32_e32 v0, 4, v36
	s_addc_u32 s5, s51, 0
	global_load_dwordx4 v[2:5], v0, s[2:3]
	global_load_dwordx4 v[6:9], v0, s[2:3] offset:1024
	global_load_dwordx4 v[10:13], v0, s[4:5]
	global_load_dwordx4 v[14:17], v0, s[4:5] offset:1024
	global_load_dwordx4 v[18:21], v0, s[2:3] offset:2048
	global_load_dwordx4 v[22:25], v0, s[2:3] offset:3072
	global_load_dwordx4 v[26:29], v0, s[4:5] offset:2048
	s_waitcnt lgkmcnt(0)
	global_load_dwordx4 v[30:33], v0, s[4:5] offset:3072
	v_ashrrev_i32_e32 v79, 31, v78
	v_readlane_b32 s8, v250, 1
	v_lshlrev_b64 v[38:39], 12, v[78:79]
	v_readlane_b32 s12, v250, 5
	v_readlane_b32 s13, v250, 6
	v_xor_b32_e32 v35, 32, v151
	v_cmp_lt_i32_e32 vcc, v35, v160
	v_lshl_add_u64 v[38:39], s[12:13], 0, v[38:39]
	v_lshl_add_u64 v[38:39], v[38:39], 0, v[0:1]
	global_load_dwordx4 v[58:61], v[38:39], off
	global_load_dwordx4 v[50:53], v[38:39], off offset:1024
	global_load_dwordx4 v[54:57], v[38:39], off offset:2048
	global_load_dwordx4 v[62:65], v[38:39], off offset:3072
	v_cndmask_b32_e32 v35, v151, v35, vcc
	v_lshlrev_b32_e32 v108, 2, v35
	v_xor_b32_e32 v35, 16, v151
	v_cmp_lt_i32_e32 vcc, v35, v160
	v_readlane_b32 s0, v254, 24
	v_readlane_b32 s9, v250, 2
	v_cndmask_b32_e32 v35, v151, v35, vcc
	v_lshlrev_b32_e32 v109, 2, v35
	v_xor_b32_e32 v35, 8, v151
	v_cmp_lt_i32_e32 vcc, v35, v160
	v_add_u32_e32 v34, s0, v34
	v_or_b32_e32 v38, 64, v36
	v_cndmask_b32_e32 v35, v151, v35, vcc
	v_lshlrev_b32_e32 v110, 2, v35
	v_xor_b32_e32 v35, 4, v151
	v_cmp_lt_i32_e32 vcc, v35, v160
	v_or_b32_e32 v40, 0x80, v36
	v_or_b32_e32 v42, 0xc0, v36
	v_cndmask_b32_e32 v35, v151, v35, vcc
	v_lshlrev_b32_e32 v111, 2, v35
	v_xor_b32_e32 v35, 2, v151
	v_cmp_lt_i32_e32 vcc, v35, v160
	v_lshlrev_b64 v[66:67], 11, v[78:79]
	v_lshl_or_b32 v66, v36, 3, v66
	v_cndmask_b32_e32 v35, v151, v35, vcc
	v_lshlrev_b32_e32 v112, 2, v35
	v_xor_b32_e32 v35, 1, v151
	v_cmp_lt_i32_e32 vcc, v35, v160
	s_mov_b64 s[8:9], 0
	v_lshlrev_b32_e32 v70, 4, v36
	v_cndmask_b32_e32 v35, v151, v35, vcc
	v_lshlrev_b32_e32 v113, 2, v35
	v_ashrrev_i32_e32 v35, 31, v34
	v_lshlrev_b64 v[68:69], 12, v[34:35]
	v_or_b32_e32 v68, v68, v0
	v_lshlrev_b32_e32 v72, 4, v38
	v_lshlrev_b32_e32 v74, 4, v40
	v_lshlrev_b32_e32 v76, 4, v42
	v_readlane_b32 s41, v250, 30
	v_readlane_b32 s42, v250, 31
	v_readlane_b32 s43, v250, 32
	v_readlane_b32 s44, v250, 33
	v_readlane_b32 s45, v250, 34
	v_readlane_b32 s46, v250, 35
	v_readlane_b32 s47, v250, 36
	v_readlane_b32 s52, v250, 41
	v_readlane_b32 s53, v250, 42
	v_readlane_b32 s54, v250, 43
	v_readlane_b32 s55, v250, 44
	v_readlane_b32 s10, v250, 3
	v_readlane_b32 s11, v250, 4
	v_readlane_b32 s14, v250, 7
	v_readlane_b32 s15, v250, 8
	s_waitcnt vmcnt(0)
	s_branch .LBB0_748
; DEVI unsigned pack2(float a, float b) { return __builtin_bit_cast(unsigned, __builtin_convertvector((f32x2_t){a, b}, bf16x2_t)); }
; DEVI void stnt4(float* p_, f32x4 v) { __builtin_nontemporal_store(v, (f32x4*)p_); }
;     ...
;     float s = 0.f, q = 0.f;
; #pragma unroll
;     for (int i = 0; i < 4; i++) {
;       s += v[i].x + v[i].y + v[i].z + v[i].w;
;       q += v[i].x * v[i].x + v[i].y * v[i].y + v[i].z * v[i].z + v[i].w * v[i].w;
;     }
; #pragma unroll
;     for (int o = 32; o > 0; o >>= 1) { const float s2 = __shfl_xor(s, o), q2 = __shfl_xor(q, o); s += s2; q += q2; }
;     const float mu = s * (1.f / 1024.f);
;     const float var = fmaxf(q * (1.f / 1024.f) - mu * mu, 0.f);
;     const float rs = rsqrtf(var + 1e-5f);
; #pragma unroll
;     for (int i = 0; i < 4; i++) {
;       float4 o;
;       o.x = (v[i].x - mu) * rs * gg[i].x + bb[i].x; o.y = (v[i].y - mu) * rs * gg[i].y + bb[i].y;
;       o.z = (v[i].z - mu) * rs * gg[i].z + bb[i].z; o.w = (v[i].w - mu) * rs * gg[i].w + bb[i].w;
;       uint2 pk; pk.x = pack2(o.x, o.y); pk.y = pack2(o.z, o.w);
;       if (mode != 2) ((uint2*)(xb + (size_t)r * 1024))[lane + 64 * i] = pk;
;       if (mode == 2) stnt4(p.out + O_Y + (size_t)r * 1024 + (size_t)(lane + 64 * i) * 4, (f32x4){o.x, o.y, o.z, o.w});
;     }
; #pragma unroll
;     for (int i = 0; i < 4; i++) v[i] = vn[i];
.LBB0_747:
	s_or_b64 exec, exec, s[10:11]
	v_mul_f32_e32 v0, v51, v51
	v_pk_fma_f32 v[80:81], v[50:51], v[50:51], v[0:1] op_sel_hi:[1,1,0]
	v_mul_f32_e32 v0, v55, v55
	v_pk_fma_f32 v[84:85], v[54:55], v[54:55], v[0:1] op_sel_hi:[1,1,0]
	v_mov_b32_e32 v94, v64
	v_mov_b32_e32 v95, v62
	v_mul_f32_e32 v0, v63, v63
	v_pk_fma_f32 v[96:97], v[62:63], v[62:63], v[0:1] op_sel_hi:[1,1,0]
	v_pk_mul_f32 v[98:99], v[64:65], v[64:65]
	v_pk_add_f32 v[94:95], v[94:95], v[62:63]
	v_mov_b32_e32 v97, v64
	v_mov_b32_e32 v99, v95
	v_mul_f32_e32 v86, v65, v65
	v_pk_add_f32 v[88:89], v[58:59], v[58:59] op_sel:[0,1] op_sel_hi:[1,0]
	v_pk_mul_f32 v[90:91], v[58:59], v[58:59]
	v_pk_mul_f32 v[92:93], v[60:61], v[60:61]
	v_pk_add_f32 v[94:95], v[98:99], v[96:97]
	v_mov_b32_e32 v87, v65
	v_pk_add_f32 v[78:79], v[50:51], v[50:51] op_sel_hi:[0,1]
	v_pk_add_f32 v[86:87], v[94:95], v[86:87]
	v_mov_b32_e32 v94, v90
	v_mov_b32_e32 v95, v88
	v_pk_mov_b32 v[88:89], v[90:91], v[60:61] op_sel:[1,0]
	v_mov_b32_e32 v90, v92
	v_mov_b32_e32 v0, v93
	v_pk_mul_f32 v[92:93], v[52:53], v[52:53]
	v_mov_b32_e32 v81, v52
	v_mov_b32_e32 v78, v92
	v_pk_add_f32 v[78:79], v[78:79], v[80:81]
	v_mov_b32_e32 v80, v93
	v_mov_b32_e32 v81, v53
	v_pk_add_f32 v[82:83], v[54:55], v[54:55] op_sel_hi:[0,1]
	v_pk_add_f32 v[88:89], v[94:95], v[88:89]
	v_mov_b32_e32 v91, v61
	v_pk_add_f32 v[78:79], v[78:79], v[80:81]
	v_pk_mul_f32 v[80:81], v[56:57], v[56:57]
	v_pk_add_f32 v[88:89], v[88:89], v[90:91]
	v_mov_b32_e32 v82, v80
	v_mov_b32_e32 v85, v56
	v_pk_add_f32 v[88:89], v[88:89], v[0:1]
	v_pk_add_f32 v[82:83], v[82:83], v[84:85]
	v_mov_b32_e32 v80, v81
	v_mov_b32_e32 v81, v57
	v_pk_add_f32 v[78:79], v[88:89], v[78:79]
	v_pk_add_f32 v[80:81], v[82:83], v[80:81]
	s_mov_b32 s0, 0x3a800000
	v_pk_add_f32 v[78:79], v[78:79], v[80:81]
	s_and_b64 s[2:3], exec, vcc
	v_pk_add_f32 v[78:79], v[78:79], v[86:87]
	ds_bpermute_b32 v81, v108, v79
	ds_bpermute_b32 v80, v108, v78
	v_readlane_b32 s40, v250, 1
	v_readlane_b32 s44, v250, 5
	v_readlane_b32 s45, v250, 6
	s_or_b64 s[8:9], s[2:3], s[8:9]
	s_waitcnt lgkmcnt(0)
	v_pk_add_f32 v[78:79], v[78:79], v[80:81]
	ds_bpermute_b32 v81, v109, v79
	ds_bpermute_b32 v80, v109, v78
	v_lshl_add_u64 v[90:91], s[44:45], 0, v[66:67]
	v_readlane_b32 s2, v254, 19
	v_readlane_b32 s3, v254, 20
	v_readlane_b32 s41, v250, 2
	s_waitcnt lgkmcnt(0)
	v_pk_add_f32 v[78:79], v[78:79], v[80:81]
	ds_bpermute_b32 v81, v110, v79
	ds_bpermute_b32 v80, v110, v78
	v_lshl_add_u64 v[66:67], v[66:67], 0, s[2:3]
	v_readlane_b32 s2, v254, 17
	v_readlane_b32 s3, v254, 18
	v_readlane_b32 s42, v250, 3
	s_waitcnt lgkmcnt(0)
	v_pk_add_f32 v[78:79], v[78:79], v[80:81]
	ds_bpermute_b32 v81, v111, v79
	ds_bpermute_b32 v80, v111, v78
	v_lshl_add_u64 v[68:69], v[68:69], 0, s[2:3]
	v_readlane_b32 s43, v250, 4
	v_readlane_b32 s46, v250, 7
	v_readlane_b32 s47, v250, 8
	s_waitcnt lgkmcnt(0)
	v_pk_add_f32 v[78:79], v[78:79], v[80:81]
	ds_bpermute_b32 v81, v112, v79
	ds_bpermute_b32 v80, v112, v78
	s_waitcnt lgkmcnt(0)
	v_pk_add_f32 v[78:79], v[78:79], v[80:81]
	ds_bpermute_b32 v81, v113, v79
	ds_bpermute_b32 v80, v113, v78
	s_waitcnt lgkmcnt(0)
	v_pk_add_f32 v[78:79], v[78:79], v[80:81]
	s_nop 0
	v_pk_mul_f32 v[78:79], v[78:79], s[0:1] op_sel_hi:[1,0]
	s_mov_b32 s0, 0x800000
	v_fma_f32 v0, -v79, v79, v78
	v_max_f32_e32 v0, 0, v0
	v_add_f32_e32 v0, 0x3727c5ac, v0
	v_cmp_gt_f32_e32 vcc, s0, v0
	v_mul_f32_e32 v71, 0x4b800000, v0
	v_pk_add_f32 v[58:59], v[58:59], v[78:79] op_sel:[0,1] neg_lo:[0,1] neg_hi:[0,1]
	v_cndmask_b32_e32 v0, v0, v71, vcc
	v_rsq_f32_e32 v0, v0
	v_pk_add_f32 v[60:61], v[60:61], v[78:79] op_sel:[0,1] neg_lo:[0,1] neg_hi:[0,1]
	v_pk_add_f32 v[50:51], v[50:51], v[78:79] op_sel:[0,1] neg_lo:[0,1] neg_hi:[0,1]
	v_pk_add_f32 v[52:53], v[52:53], v[78:79] op_sel:[0,1] neg_lo:[0,1] neg_hi:[0,1]
	v_mul_f32_e32 v71, 0x45800000, v0
	v_cndmask_b32_e32 v0, v0, v71, vcc
	v_pk_mul_f32 v[58:59], v[58:59], v[0:1] op_sel_hi:[1,0]
	v_pk_mul_f32 v[60:61], v[60:61], v[0:1] op_sel_hi:[1,0]
	v_pk_fma_f32 v[58:59], v[2:3], v[58:59], v[10:11]
	v_pk_fma_f32 v[60:61], v[4:5], v[60:61], v[12:13]
	s_mov_b32 s0, 0x4200000
	v_pk_mul_f32 v[50:51], v[50:51], v[0:1] op_sel_hi:[1,0]
	v_pk_mul_f32 v[52:53], v[52:53], v[0:1] op_sel_hi:[1,0]
	v_cvt_pk_bf16_f32 v61, v60, v61
	v_cvt_pk_bf16_f32 v60, v58, v59
	v_add_co_u32_e32 v58, vcc, s0, v90
	v_pk_fma_f32 v[50:51], v[6:7], v[50:51], v[14:15]
	v_pk_fma_f32 v[52:53], v[8:9], v[52:53], v[16:17]
	v_addc_co_u32_e32 v59, vcc, 0, v91, vcc
	v_cvt_pk_bf16_f32 v53, v52, v53
	v_cvt_pk_bf16_f32 v52, v50, v51
	global_store_dwordx2 v[58:59], v[52:53], off offset:512
	v_pk_add_f32 v[50:51], v[54:55], v[78:79] op_sel:[0,1] neg_lo:[0,1] neg_hi:[0,1]
	v_pk_add_f32 v[52:53], v[56:57], v[78:79] op_sel:[0,1] neg_lo:[0,1] neg_hi:[0,1]
	v_pk_mul_f32 v[50:51], v[50:51], v[0:1] op_sel_hi:[1,0]
	v_pk_mul_f32 v[52:53], v[52:53], v[0:1] op_sel_hi:[1,0]
	v_pk_fma_f32 v[50:51], v[18:19], v[50:51], v[26:27]
	v_pk_fma_f32 v[52:53], v[20:21], v[52:53], v[28:29]
	global_store_dwordx2 v[58:59], v[60:61], off
	v_cvt_pk_bf16_f32 v53, v52, v53
	v_cvt_pk_bf16_f32 v52, v50, v51
	global_store_dwordx2 v[58:59], v[52:53], off offset:1024
	v_pk_add_f32 v[50:51], v[62:63], v[78:79] op_sel:[0,1] neg_lo:[0,1] neg_hi:[0,1]
	v_pk_add_f32 v[52:53], v[64:65], v[78:79] op_sel:[0,1] neg_lo:[0,1] neg_hi:[0,1]
	v_pk_mul_f32 v[50:51], v[50:51], v[0:1] op_sel_hi:[1,0]
	v_pk_mul_f32 v[52:53], v[52:53], v[0:1] op_sel_hi:[1,0]
	v_pk_fma_f32 v[50:51], v[22:23], v[50:51], v[30:31]
	v_pk_fma_f32 v[52:53], v[24:25], v[52:53], v[32:33]
	v_mov_b32_e32 v78, v114
	v_cvt_pk_bf16_f32 v53, v52, v53
	v_cvt_pk_bf16_f32 v52, v50, v51
	global_store_dwordx2 v[58:59], v[52:53], off offset:1536
	s_waitcnt vmcnt(4)
	v_mov_b64_e32 v[58:59], v[34:35]
	v_mov_b64_e32 v[60:61], v[36:37]
	v_mov_b64_e32 v[50:51], v[38:39]
	v_mov_b64_e32 v[52:53], v[40:41]
	v_mov_b64_e32 v[54:55], v[42:43]
	v_mov_b64_e32 v[56:57], v[44:45]
	v_mov_b64_e32 v[62:63], v[46:47]
	v_mov_b64_e32 v[64:65], v[48:49]
	s_andn2_b64 exec, exec, s[8:9]
	s_cbranch_execz .LBB0_752
